# combination: attention DMA placement + saddr-form LDS-DMA in 7 GEMM loops + phase-0 weight conversion offload (2000 items per idle half-round)
# speedup vs baseline: 1.0090x; 1.0090x over previous
.LBB0_20:
	s_lshr_b32 s89, s77, 6
	s_load_dwordx16 s[8:23], s[0:1], 0x40
	s_cmp_lt_i32 s28, 1
	s_cselect_b64 s[0:1], -1, 0
	s_cmp_gt_i32 s29, 0
	s_cselect_b64 s[2:3], -1, 0
	s_and_b64 s[2:3], s[0:1], s[2:3]
	s_andn2_b64 vcc, exec, s[2:3]
	v_and_b32_e32 v227, 63, v226
	s_cbranch_vccnz .LBB0_42
	s_mov_b32 s96, 0
	s_mov_b32 s97, 0x4090
	s_lshl_b32 s0, s76, 3
	s_add_i32 s4, s0, s89

.Lp0call_1:
	v_writelane_b32 v251, s0, 0
	v_writelane_b32 v251, s1, 1
	v_writelane_b32 v251, s4, 2
	v_writelane_b32 v251, s5, 3
	v_writelane_b32 v251, s26, 4
	v_writelane_b32 v251, s27, 5
	v_writelane_b32 v251, s30, 6
	v_writelane_b32 v251, s31, 7
	v_writelane_b32 v251, s34, 8
	v_writelane_b32 v251, s35, 9
	v_writelane_b32 v251, s52, 10
	v_writelane_b32 v251, s53, 11
	v_writelane_b32 v251, s54, 12
	v_writelane_b32 v251, s55, 13
	v_writelane_b32 v251, s56, 14
	v_writelane_b32 v251, s57, 15
	v_writelane_b32 v251, s58, 16
	v_writelane_b32 v251, s59, 17
	v_writelane_b32 v251, s60, 18
	v_writelane_b32 v251, s61, 19
	v_writelane_b32 v251, s62, 20
	v_writelane_b32 v251, s63, 21
	v_writelane_b32 v251, s64, 22
	v_writelane_b32 v251, s65, 23
	v_writelane_b32 v251, s66, 24
	v_writelane_b32 v251, s67, 25
	v_writelane_b32 v251, s68, 26
	v_writelane_b32 v251, s69, 27
	v_writelane_b32 v251, s70, 28
	v_writelane_b32 v251, s71, 29
	v_writelane_b32 v251, s33, 30
	v_writelane_b32 v251, s40, 31
	v_writelane_b32 v251, s41, 32
	v_writelane_b32 v251, s42, 33
	v_writelane_b32 v251, s43, 34
	v_writelane_b32 v251, s89, 35
	v_writelane_b32 v251, vcc_lo, 36
	v_writelane_b32 v251, vcc_hi, 37
	s_nop 1
	v_readlane_b32 s0, v250, 0
	v_readlane_b32 s1, v250, 1
	s_nop 3
	s_sub_u32 s0, s0, 0x90
	s_subb_u32 s1, s1, 0
	s_load_dwordx4 s[40:43], s[0:1], 0x10
	s_lshr_b32 s89, s77, 6
	s_sub_i32 s4, s6, 0x80
	s_lshl_b32 s4, s4, 3
	s_add_i32 s4, s4, s89
	s_add_i32 s4, s4, 0x4090
	s_mov_b32 s33, 0x80
	s_mov_b32 s97, 0x4860
	s_mov_b32 s96, 1
	s_waitcnt vmcnt(0) lgkmcnt(0)
	s_branch .Lp0_entry

.Lp0call_2:
	v_writelane_b32 v251, s0, 0
	v_writelane_b32 v251, s1, 1
	v_writelane_b32 v251, s4, 2
	v_writelane_b32 v251, s5, 3
	v_writelane_b32 v251, s26, 4
	v_writelane_b32 v251, s27, 5
	v_writelane_b32 v251, s30, 6
	v_writelane_b32 v251, s31, 7
	v_writelane_b32 v251, s34, 8
	v_writelane_b32 v251, s35, 9
	v_writelane_b32 v251, s52, 10
	v_writelane_b32 v251, s53, 11
	v_writelane_b32 v251, s54, 12
	v_writelane_b32 v251, s55, 13
	v_writelane_b32 v251, s56, 14
	v_writelane_b32 v251, s57, 15
	v_writelane_b32 v251, s58, 16
	v_writelane_b32 v251, s59, 17
	v_writelane_b32 v251, s60, 18
	v_writelane_b32 v251, s61, 19
	v_writelane_b32 v251, s62, 20
	v_writelane_b32 v251, s63, 21
	v_writelane_b32 v251, s64, 22
	v_writelane_b32 v251, s65, 23
	v_writelane_b32 v251, s66, 24
	v_writelane_b32 v251, s67, 25
	v_writelane_b32 v251, s68, 26
	v_writelane_b32 v251, s69, 27
	v_writelane_b32 v251, s70, 28
	v_writelane_b32 v251, s71, 29
	v_writelane_b32 v251, s33, 30
	v_writelane_b32 v251, s40, 31
	v_writelane_b32 v251, s41, 32
	v_writelane_b32 v251, s42, 33
	v_writelane_b32 v251, s43, 34
	v_writelane_b32 v251, s89, 35
	v_writelane_b32 v251, vcc_lo, 36
	v_writelane_b32 v251, vcc_hi, 37
	s_nop 1
	v_readlane_b32 s0, v250, 0
	v_readlane_b32 s1, v250, 1
	s_nop 3
	s_sub_u32 s0, s0, 0x90
	s_subb_u32 s1, s1, 0
	s_load_dwordx4 s[40:43], s[0:1], 0x10
	s_lshr_b32 s89, s77, 6
	s_sub_i32 s4, s6, 0x80
	s_lshl_b32 s4, s4, 3
	s_add_i32 s4, s4, s89
	s_add_i32 s4, s4, 0x4860
	s_mov_b32 s33, 0x80
	s_mov_b32 s97, 0x5030
	s_mov_b32 s96, 2
	s_waitcnt vmcnt(0) lgkmcnt(0)
	s_branch .Lp0_entry

.Lp0call_3:
	v_writelane_b32 v251, s0, 0
	v_writelane_b32 v251, s1, 1
	v_writelane_b32 v251, s4, 2
	v_writelane_b32 v251, s5, 3
	v_writelane_b32 v251, s26, 4
	v_writelane_b32 v251, s27, 5
	v_writelane_b32 v251, s30, 6
	v_writelane_b32 v251, s31, 7
	v_writelane_b32 v251, s34, 8
	v_writelane_b32 v251, s35, 9
	v_writelane_b32 v251, s52, 10
	v_writelane_b32 v251, s53, 11
	v_writelane_b32 v251, s54, 12
	v_writelane_b32 v251, s55, 13
	v_writelane_b32 v251, s56, 14
	v_writelane_b32 v251, s57, 15
	v_writelane_b32 v251, s58, 16
	v_writelane_b32 v251, s59, 17
	v_writelane_b32 v251, s60, 18
	v_writelane_b32 v251, s61, 19
	v_writelane_b32 v251, s62, 20
	v_writelane_b32 v251, s63, 21
	v_writelane_b32 v251, s64, 22
	v_writelane_b32 v251, s65, 23
	v_writelane_b32 v251, s66, 24
	v_writelane_b32 v251, s67, 25
	v_writelane_b32 v251, s68, 26
	v_writelane_b32 v251, s69, 27
	v_writelane_b32 v251, s70, 28
	v_writelane_b32 v251, s71, 29
	v_writelane_b32 v251, s33, 30
	v_writelane_b32 v251, s40, 31
	v_writelane_b32 v251, s41, 32
	v_writelane_b32 v251, s42, 33
	v_writelane_b32 v251, s43, 34
	v_writelane_b32 v251, s89, 35
	v_writelane_b32 v251, vcc_lo, 36
	v_writelane_b32 v251, vcc_hi, 37
	s_nop 1
	v_readlane_b32 s0, v250, 0
	v_readlane_b32 s1, v250, 1
	s_nop 3
	s_sub_u32 s0, s0, 0x90
	s_subb_u32 s1, s1, 0
	s_load_dwordx4 s[40:43], s[0:1], 0x10
	s_lshr_b32 s89, s77, 6
	s_sub_i32 s4, s6, 0x80
	s_lshl_b32 s4, s4, 3
	s_add_i32 s4, s4, s89
	s_add_i32 s4, s4, 0x5030
	s_mov_b32 s33, 0x80
	s_mov_b32 s97, 0x5800
	s_mov_b32 s96, 3
	s_waitcnt vmcnt(0) lgkmcnt(0)
	s_branch .Lp0_entry
